# swiglu epilogue: 8 serialized rstd (ssq) loads issued together before the align barrier
# speedup vs baseline: 1.0080x; 1.0080x over previous
.Lswi_pref:
	v_lshl_add_u32 v236, s38, 8, v142
	v_ashrrev_i32_e32 v237, 31, v236
	v_lshlrev_b64 v[236:237], 6, v[236:237]
	v_lshl_add_u64 v[236:237], v[144:145], 0, v[236:237]
	global_load_dwordx4 v[204:207], v[236:237], off
	global_load_dwordx4 v[208:211], v[236:237], off offset:1024
	global_load_dwordx4 v[212:215], v[236:237], off offset:2048
	global_load_dwordx4 v[216:219], v[236:237], off offset:3072
	v_add_co_u32_e32 v236, vcc, 0x2000, v236
	s_nop 1
	v_addc_co_u32_e32 v237, vcc, 0, v237, vcc
	global_load_dwordx4 v[220:223], v[236:237], off
	global_load_dwordx4 v[224:227], v[236:237], off offset:1024
	global_load_dwordx4 v[228:231], v[236:237], off offset:2048
	global_load_dwordx4 v[232:235], v[236:237], off offset:3072
	s_and_b64 vcc, exec, s[52:53]
	s_cbranch_vccz .LBB7_360

.LBB7_360:
	v_and_b32_e32 v131, 64, v163
	v_xor_b32_e32 v130, 16, v163
	v_add_u32_e32 v131, 64, v131
	v_cmp_lt_i32_e32 vcc, v130, v131
	v_lshl_add_u32 v132, s38, 8, v142
	v_ashrrev_i32_e32 v133, 31, v132
	v_cndmask_b32_e32 v130, v163, v130, vcc
	v_lshlrev_b32_e32 v183, 2, v130
	v_xor_b32_e32 v130, 32, v163
	v_cmp_lt_i32_e32 vcc, v130, v131
	v_or_b32_e32 v172, 16, v132
	v_ashrrev_i32_e32 v173, 31, v172
	v_cndmask_b32_e32 v130, v163, v130, vcc
	v_lshlrev_b32_e32 v181, 2, v130
	v_lshlrev_b64 v[130:131], 6, v[132:133]
	v_lshl_add_u64 v[130:131], v[144:145], 0, v[130:131]
	v_lshlrev_b64 v[172:173], 6, v[172:173]
	v_lshl_add_u64 v[172:173], v[144:145], 0, v[172:173]
	s_lshl_b32 s9, s10, 7
	s_mov_b32 s10, 0x358637bd
	v_mov_b64_e32 v[190:191], s[10:11]
	s_movk_i32 s10, 0x2000
	s_or_b32 s9, s9, s96
	s_ashr_i32 s16, s9, 6
	s_ashr_i32 s17, s16, 31
	s_mul_i32 s13, s38, 0x160000
	s_lshl_b64 s[16:17], s[16:17], 15
	s_add_u32 s9, s70, s13
	s_waitcnt vmcnt(0)
	v_mov_b64_e32 v[184:185], v[204:205]
	v_mov_b64_e32 v[186:187], v[206:207]
	v_mov_b32_e32 v170, v185
	v_mov_b32_e32 v171, v186
	v_mov_b32_e32 v185, v187
	v_pk_add_f32 v[170:171], v[170:171], v[184:185]
	v_mov_b64_e32 v[184:185], v[208:209]
	v_mov_b64_e32 v[186:187], v[210:211]
	v_mov_b32_e32 v172, v185
	v_mov_b32_e32 v173, v186
	v_mov_b32_e32 v185, v187
	v_pk_add_f32 v[172:173], v[172:173], v[184:185]
	v_mov_b32_e32 v185, v170
	v_mov_b32_e32 v184, v172
	v_mov_b32_e32 v170, v173
	v_pk_add_f32 v[170:171], v[184:185], v[170:171]
	ds_bpermute_b32 v173, v183, v171
	ds_bpermute_b32 v172, v183, v170
	s_waitcnt lgkmcnt(0)
	v_pk_add_f32 v[170:171], v[170:171], v[172:173]
	ds_bpermute_b32 v173, v181, v171
	ds_bpermute_b32 v172, v181, v170
	s_waitcnt lgkmcnt(0)
	v_pk_add_f32 v[170:171], v[170:171], v[172:173]
	s_nop 0
	v_pk_fma_f32 v[170:171], v[170:171], s[26:27], v[190:191] op_sel_hi:[1,0,0]
	s_nop 0
	v_mul_f32_e32 v133, 0x4b800000, v171
	v_cmp_gt_f32_e64 s[42:43], s11, v171
	v_cmp_gt_f32_e32 vcc, s11, v170
	s_nop 0
	v_cndmask_b32_e64 v133, v171, v133, s[42:43]
	v_rsq_f32_e32 v133, v133
	s_nop 0
	v_mul_f32_e32 v171, 0x45800000, v133
	v_cndmask_b32_e64 v188, v133, v171, s[42:43]
	v_mul_f32_e32 v133, 0x4b800000, v170
	v_cndmask_b32_e32 v133, v170, v133, vcc
	v_rsq_f32_e32 v133, v133
	v_pk_mul_f32 v[126:127], v[126:127], v[188:189] op_sel_hi:[1,0]
	v_pk_mul_f32 v[122:123], v[122:123], v[188:189] op_sel_hi:[1,0]
	v_pk_mul_f32 v[124:125], v[124:125], v[188:189] op_sel_hi:[1,0]
	v_mul_f32_e32 v170, 0x45800000, v133
	v_cndmask_b32_e32 v186, v133, v170, vcc
	v_or_b32_e32 v170, 32, v132
	v_ashrrev_i32_e32 v171, 31, v170
	v_lshlrev_b64 v[170:171], 6, v[170:171]
	v_lshl_add_u64 v[170:171], v[144:145], 0, v[170:171]
	v_or_b32_e32 v132, 48, v132
	v_ashrrev_i32_e32 v133, 31, v132
	v_lshlrev_b64 v[132:133], 6, v[132:133]
	v_lshl_add_u64 v[132:133], v[144:145], 0, v[132:133]
	v_pk_mul_f32 v[122:123], v[126:127], v[122:123]
	v_pk_mul_f32 v[118:119], v[118:119], v[188:189] op_sel_hi:[1,0]
	v_pk_mul_f32 v[114:115], v[114:115], v[188:189] op_sel_hi:[1,0]
	v_pk_mul_f32 v[116:117], v[116:117], v[188:189] op_sel_hi:[1,0]
	v_pk_mul_f32 v[114:115], v[118:119], v[114:115]
	v_pk_mul_f32 v[110:111], v[110:111], v[186:187] op_sel_hi:[1,0]
	v_pk_mul_f32 v[106:107], v[106:107], v[186:187] op_sel_hi:[1,0]
	v_pk_mul_f32 v[108:109], v[108:109], v[186:187] op_sel_hi:[1,0]
	v_pk_mul_f32 v[106:107], v[110:111], v[106:107]
	v_pk_mul_f32 v[102:103], v[102:103], v[186:187] op_sel_hi:[1,0]
	v_pk_mul_f32 v[98:99], v[98:99], v[186:187] op_sel_hi:[1,0]
	v_pk_mul_f32 v[100:101], v[100:101], v[186:187] op_sel_hi:[1,0]
	v_pk_mul_f32 v[98:99], v[102:103], v[98:99]
	v_mov_b64_e32 v[192:193], v[212:213]
	v_mov_b64_e32 v[194:195], v[214:215]
	v_mov_b32_e32 v170, v193
	v_mov_b32_e32 v171, v194
	v_mov_b32_e32 v193, v195
	v_pk_add_f32 v[170:171], v[170:171], v[192:193]
	v_mov_b64_e32 v[192:193], v[216:217]
	v_mov_b64_e32 v[194:195], v[218:219]
	v_mov_b32_e32 v173, v170
	v_mov_b32_e32 v132, v193
	v_mov_b32_e32 v133, v194
	v_mov_b32_e32 v193, v195
	v_pk_add_f32 v[132:133], v[132:133], v[192:193]
	s_nop 0
	v_mov_b32_e32 v172, v132
	v_mov_b32_e32 v170, v133
	v_pk_add_f32 v[132:133], v[172:173], v[170:171]
	ds_bpermute_b32 v171, v183, v133
	ds_bpermute_b32 v170, v183, v132
	s_waitcnt lgkmcnt(0)
	v_pk_add_f32 v[132:133], v[132:133], v[170:171]
	ds_bpermute_b32 v171, v181, v133
	ds_bpermute_b32 v170, v181, v132
	s_waitcnt lgkmcnt(0)
	v_pk_add_f32 v[132:133], v[132:133], v[170:171]
	s_nop 0
	v_pk_fma_f32 v[132:133], v[132:133], s[26:27], v[190:191] op_sel_hi:[1,0,0]
	s_nop 0
	v_mul_f32_e32 v170, 0x4b800000, v133
	v_cmp_gt_f32_e64 s[42:43], s11, v133
	v_cmp_gt_f32_e32 vcc, s11, v132
	s_nop 0
	v_cndmask_b32_e64 v133, v133, v170, s[42:43]
	v_rsq_f32_e32 v133, v133
	s_nop 0
	v_mul_f32_e32 v170, 0x45800000, v133
	v_cndmask_b32_e64 v184, v133, v170, s[42:43]
	v_mul_f32_e32 v133, 0x4b800000, v132
	v_cndmask_b32_e32 v132, v132, v133, vcc
	v_rsq_f32_e32 v132, v132
	v_pk_mul_f32 v[94:95], v[94:95], v[184:185] op_sel_hi:[1,0]
	v_pk_mul_f32 v[90:91], v[90:91], v[184:185] op_sel_hi:[1,0]
	v_pk_mul_f32 v[92:93], v[92:93], v[184:185] op_sel_hi:[1,0]
	v_mul_f32_e32 v133, 0x45800000, v132
	v_cndmask_b32_e32 v182, v132, v133, vcc
	v_add_co_u32_e32 v170, vcc, s10, v130
	s_mul_hi_i32 s10, s38, 0x160000
	s_nop 0
	v_addc_co_u32_e32 v171, vcc, 0, v131, vcc
	s_addc_u32 s10, s71, s10
	s_add_u32 s16, s9, s16
	s_addc_u32 s17, s10, s17
	v_pk_mul_f32 v[90:91], v[94:95], v[90:91]
	v_pk_mul_f32 v[86:87], v[86:87], v[184:185] op_sel_hi:[1,0]
	v_pk_mul_f32 v[82:83], v[82:83], v[184:185] op_sel_hi:[1,0]
	v_pk_mul_f32 v[84:85], v[84:85], v[184:185] op_sel_hi:[1,0]
	v_pk_mul_f32 v[82:83], v[86:87], v[82:83]
	v_pk_mul_f32 v[78:79], v[78:79], v[182:183] op_sel_hi:[1,0]
	v_pk_mul_f32 v[74:75], v[74:75], v[182:183] op_sel_hi:[1,0]
	v_pk_mul_f32 v[76:77], v[76:77], v[182:183] op_sel_hi:[1,0]
	v_pk_mul_f32 v[74:75], v[78:79], v[74:75]
	v_pk_mul_f32 v[70:71], v[70:71], v[182:183] op_sel_hi:[1,0]
	v_pk_mul_f32 v[66:67], v[66:67], v[182:183] op_sel_hi:[1,0]
	v_pk_mul_f32 v[68:69], v[68:69], v[182:183] op_sel_hi:[1,0]
	v_pk_mul_f32 v[66:67], v[70:71], v[66:67]
	v_mov_b64_e32 v[130:131], v[220:221]
	v_mov_b64_e32 v[132:133], v[222:223]
	v_mov_b32_e32 v172, v131
	v_mov_b32_e32 v173, v132
	v_mov_b32_e32 v131, v133
	v_pk_add_f32 v[172:173], v[172:173], v[130:131]
	v_mov_b64_e32 v[130:131], v[224:225]
	v_mov_b64_e32 v[132:133], v[226:227]
	v_mov_b32_e32 v192, v131
	v_mov_b32_e32 v193, v132
	v_mov_b32_e32 v131, v133
	v_pk_add_f32 v[130:131], v[192:193], v[130:131]
	v_mov_b32_e32 v133, v172
	v_mov_b32_e32 v132, v130
	v_mov_b32_e32 v172, v131
	v_pk_add_f32 v[130:131], v[132:133], v[172:173]
	ds_bpermute_b32 v133, v183, v131
	ds_bpermute_b32 v132, v183, v130
	s_waitcnt lgkmcnt(0)
	v_pk_add_f32 v[130:131], v[130:131], v[132:133]
	ds_bpermute_b32 v133, v181, v131
	ds_bpermute_b32 v132, v181, v130
	s_waitcnt lgkmcnt(0)
	v_pk_add_f32 v[130:131], v[130:131], v[132:133]
	s_nop 0
	v_pk_fma_f32 v[130:131], v[130:131], s[26:27], v[190:191] op_sel_hi:[1,0,0]
	s_nop 0
	v_mul_f32_e32 v132, 0x4b800000, v131
	v_cmp_gt_f32_e64 s[42:43], s11, v131
	v_cmp_gt_f32_e32 vcc, s11, v130
	s_nop 0
	v_cndmask_b32_e64 v131, v131, v132, s[42:43]
	v_rsq_f32_e32 v131, v131
	s_nop 0
	v_mul_f32_e32 v132, 0x45800000, v131
	v_cndmask_b32_e64 v180, v131, v132, s[42:43]
	v_mul_f32_e32 v131, 0x4b800000, v130
	v_cndmask_b32_e32 v130, v130, v131, vcc
	v_rsq_f32_e32 v130, v130
	v_pk_mul_f32 v[62:63], v[62:63], v[180:181] op_sel_hi:[1,0]
	v_pk_mul_f32 v[58:59], v[58:59], v[180:181] op_sel_hi:[1,0]
	v_pk_mul_f32 v[60:61], v[60:61], v[180:181] op_sel_hi:[1,0]
	v_mul_f32_e32 v131, 0x45800000, v130
	v_cndmask_b32_e32 v178, v130, v131, vcc
	v_pk_mul_f32 v[58:59], v[62:63], v[58:59]
	v_pk_mul_f32 v[54:55], v[54:55], v[180:181] op_sel_hi:[1,0]
	v_pk_mul_f32 v[50:51], v[50:51], v[180:181] op_sel_hi:[1,0]
	v_pk_mul_f32 v[52:53], v[52:53], v[180:181] op_sel_hi:[1,0]
	v_pk_mul_f32 v[50:51], v[54:55], v[50:51]
	v_pk_mul_f32 v[46:47], v[46:47], v[178:179] op_sel_hi:[1,0]
	v_pk_mul_f32 v[42:43], v[42:43], v[178:179] op_sel_hi:[1,0]
	v_pk_mul_f32 v[44:45], v[44:45], v[178:179] op_sel_hi:[1,0]
	v_pk_mul_f32 v[42:43], v[46:47], v[42:43]
	v_pk_mul_f32 v[38:39], v[38:39], v[178:179] op_sel_hi:[1,0]
	v_pk_mul_f32 v[34:35], v[34:35], v[178:179] op_sel_hi:[1,0]
	v_pk_mul_f32 v[36:37], v[36:37], v[178:179] op_sel_hi:[1,0]
	v_pk_mul_f32 v[34:35], v[38:39], v[34:35]
	v_mov_b64_e32 v[130:131], v[228:229]
	v_mov_b64_e32 v[132:133], v[230:231]
	v_mov_b32_e32 v172, v131
	v_mov_b32_e32 v173, v132
	v_mov_b32_e32 v131, v133
	v_pk_add_f32 v[192:193], v[172:173], v[130:131]
	v_mov_b64_e32 v[130:131], v[232:233]
	v_mov_b64_e32 v[132:133], v[234:235]
	v_mov_b32_e32 v170, v131
	v_mov_b32_e32 v171, v132
	v_mov_b32_e32 v131, v133
	v_pk_add_f32 v[130:131], v[170:171], v[130:131]
	v_pk_mul_f32 v[170:171], v[126:127], s[30:31] op_sel_hi:[1,0]
	v_pk_mul_f32 v[126:127], v[128:129], v[188:189] op_sel_hi:[1,0]
	v_exp_f32_e32 v170, v170
	v_pk_mul_f32 v[128:129], v[126:127], s[30:31] op_sel_hi:[1,0]
	v_exp_f32_e32 v171, v171
	v_exp_f32_e32 v128, v128
	v_exp_f32_e32 v129, v129
	v_pk_mul_f32 v[124:125], v[126:127], v[124:125]
	v_pk_add_f32 v[170:171], v[170:171], 1.0 op_sel_hi:[1,0]
	v_mov_b32_e32 v132, v130
	v_pk_add_f32 v[128:129], v[128:129], 1.0 op_sel_hi:[1,0]
	v_rcp_f32_e32 v170, v170
	v_rcp_f32_e32 v171, v171
	v_rcp_f32_e32 v128, v128
	v_rcp_f32_e32 v129, v129
	v_mov_b32_e32 v133, v192
	v_pk_mul_f32 v[122:123], v[122:123], v[170:171]
	v_mov_b32_e32 v192, v131
	v_pk_mul_f32 v[124:125], v[124:125], v[128:129]
	v_cvt_pk_bf16_f32 v122, v122, v123
	v_pk_add_f32 v[130:131], v[132:133], v[192:193]
	v_cvt_pk_bf16_f32 v123, v124, v125
	v_pk_mul_f32 v[124:125], v[118:119], s[30:31] op_sel_hi:[1,0]
	ds_bpermute_b32 v133, v183, v131
	v_exp_f32_e32 v124, v124
	v_exp_f32_e32 v125, v125
	ds_bpermute_b32 v132, v183, v130
	v_pk_add_f32 v[124:125], v[124:125], 1.0 op_sel_hi:[1,0]
	s_nop 0
	v_rcp_f32_e32 v124, v124
	v_rcp_f32_e32 v125, v125
	s_waitcnt lgkmcnt(0)
	v_pk_add_f32 v[130:131], v[130:131], v[132:133]
	ds_bpermute_b32 v133, v181, v131
	ds_bpermute_b32 v132, v181, v130
	v_pk_mul_f32 v[114:115], v[114:115], v[124:125]
	s_waitcnt lgkmcnt(0)
	v_pk_add_f32 v[130:131], v[130:131], v[132:133]
	v_cvt_pk_bf16_f32 v124, v114, v115
	v_pk_mul_f32 v[114:115], v[120:121], v[188:189] op_sel_hi:[1,0]
	v_pk_fma_f32 v[130:131], v[130:131], s[26:27], v[190:191] op_sel_hi:[1,0,0]
	v_pk_mul_f32 v[118:119], v[114:115], s[30:31] op_sel_hi:[1,0]
	v_pk_mul_f32 v[114:115], v[114:115], v[116:117]
	v_exp_f32_e32 v118, v118
	v_exp_f32_e32 v119, v119
	v_mul_f32_e32 v132, 0x4b800000, v131
	v_cmp_gt_f32_e64 s[42:43], s11, v131
	v_cmp_gt_f32_e32 vcc, s11, v130
	v_pk_add_f32 v[118:119], v[118:119], 1.0 op_sel_hi:[1,0]
	v_cndmask_b32_e64 v131, v131, v132, s[42:43]
	v_rcp_f32_e32 v118, v118
	v_rcp_f32_e32 v119, v119
	v_rsq_f32_e32 v131, v131
	v_pk_mul_f32 v[114:115], v[114:115], v[118:119]
	s_nop 0
	v_cvt_pk_bf16_f32 v125, v114, v115
	v_lshl_add_u64 v[114:115], s[16:17], 0, v[146:147]
	v_lshl_add_u64 v[114:115], v[114:115], 0, v[0:1]
	global_store_dwordx4 v[114:115], v[122:125], off nt
	v_pk_mul_f32 v[114:115], v[110:111], s[30:31] op_sel_hi:[1,0]
	v_pk_mul_f32 v[110:111], v[112:113], v[186:187] op_sel_hi:[1,0]
	v_exp_f32_e32 v114, v114
	v_pk_mul_f32 v[112:113], v[110:111], s[30:31] op_sel_hi:[1,0]
	v_exp_f32_e32 v115, v115
	v_exp_f32_e32 v112, v112
	v_exp_f32_e32 v113, v113
	v_pk_mul_f32 v[108:109], v[110:111], v[108:109]
	v_pk_add_f32 v[114:115], v[114:115], 1.0 op_sel_hi:[1,0]
	v_pk_add_f32 v[112:113], v[112:113], 1.0 op_sel_hi:[1,0]
	v_rcp_f32_e32 v114, v114
	v_rcp_f32_e32 v115, v115
	v_rcp_f32_e32 v112, v112
	v_rcp_f32_e32 v113, v113
	v_mul_f32_e32 v132, 0x45800000, v131
	v_pk_mul_f32 v[106:107], v[106:107], v[114:115]
	v_cndmask_b32_e64 v132, v131, v132, s[42:43]
	v_pk_mul_f32 v[108:109], v[108:109], v[112:113]
	v_cvt_pk_bf16_f32 v106, v106, v107
	v_pk_mul_f32 v[30:31], v[30:31], v[132:133] op_sel_hi:[1,0]
	v_cvt_pk_bf16_f32 v107, v108, v109
	v_pk_mul_f32 v[108:109], v[102:103], s[30:31] op_sel_hi:[1,0]
	v_pk_mul_f32 v[26:27], v[26:27], v[132:133] op_sel_hi:[1,0]
	v_exp_f32_e32 v108, v108
	v_exp_f32_e32 v109, v109
	v_pk_mul_f32 v[26:27], v[30:31], v[26:27]
	v_pk_mul_f32 v[28:29], v[28:29], v[132:133] op_sel_hi:[1,0]
	v_pk_mul_f32 v[22:23], v[22:23], v[132:133] op_sel_hi:[1,0]
	v_pk_add_f32 v[108:109], v[108:109], 1.0 op_sel_hi:[1,0]
	v_pk_mul_f32 v[18:19], v[18:19], v[132:133] op_sel_hi:[1,0]
	v_rcp_f32_e32 v108, v108
	v_rcp_f32_e32 v109, v109
	v_pk_mul_f32 v[18:19], v[22:23], v[18:19]
	v_mul_f32_e32 v131, 0x4b800000, v130
	v_cndmask_b32_e32 v130, v130, v131, vcc
	v_pk_mul_f32 v[98:99], v[98:99], v[108:109]
	v_rsq_f32_e32 v130, v130
	v_cvt_pk_bf16_f32 v108, v98, v99
	v_pk_mul_f32 v[98:99], v[104:105], v[186:187] op_sel_hi:[1,0]
	v_pk_mul_f32 v[20:21], v[20:21], v[132:133] op_sel_hi:[1,0]
	v_pk_mul_f32 v[102:103], v[98:99], s[30:31] op_sel_hi:[1,0]
	v_pk_mul_f32 v[98:99], v[98:99], v[100:101]
	v_exp_f32_e32 v102, v102
	v_exp_f32_e32 v103, v103
	v_mul_f32_e32 v131, 0x45800000, v130
	v_cndmask_b32_e32 v130, v130, v131, vcc
	v_pk_mul_f32 v[14:15], v[14:15], v[130:131] op_sel_hi:[1,0]
	v_pk_add_f32 v[102:103], v[102:103], 1.0 op_sel_hi:[1,0]
	v_pk_mul_f32 v[10:11], v[10:11], v[130:131] op_sel_hi:[1,0]
	v_rcp_f32_e32 v102, v102
	v_rcp_f32_e32 v103, v103
	v_pk_mul_f32 v[10:11], v[14:15], v[10:11]
	v_pk_mul_f32 v[12:13], v[12:13], v[130:131] op_sel_hi:[1,0]
	v_pk_mul_f32 v[6:7], v[6:7], v[130:131] op_sel_hi:[1,0]
	v_pk_mul_f32 v[98:99], v[98:99], v[102:103]
	v_pk_mul_f32 v[2:3], v[2:3], v[130:131] op_sel_hi:[1,0]
	v_cvt_pk_bf16_f32 v109, v98, v99
	v_lshl_add_u64 v[98:99], s[16:17], 0, v[148:149]
	v_lshl_add_u64 v[98:99], v[98:99], 0, v[0:1]
	global_store_dwordx4 v[98:99], v[106:109], off nt
	v_pk_mul_f32 v[98:99], v[94:95], s[30:31] op_sel_hi:[1,0]
	v_pk_mul_f32 v[94:95], v[96:97], v[184:185] op_sel_hi:[1,0]
	v_exp_f32_e32 v98, v98
	v_pk_mul_f32 v[96:97], v[94:95], s[30:31] op_sel_hi:[1,0]
	v_exp_f32_e32 v99, v99
	v_exp_f32_e32 v96, v96
	v_exp_f32_e32 v97, v97
	v_pk_mul_f32 v[92:93], v[94:95], v[92:93]
	v_pk_add_f32 v[98:99], v[98:99], 1.0 op_sel_hi:[1,0]
	v_pk_add_f32 v[96:97], v[96:97], 1.0 op_sel_hi:[1,0]
	v_rcp_f32_e32 v98, v98
	v_rcp_f32_e32 v99, v99
	v_rcp_f32_e32 v96, v96
	v_rcp_f32_e32 v97, v97
	v_pk_mul_f32 v[2:3], v[6:7], v[2:3]
	v_pk_mul_f32 v[90:91], v[90:91], v[98:99]
	v_pk_mul_f32 v[4:5], v[4:5], v[130:131] op_sel_hi:[1,0]
	v_pk_mul_f32 v[92:93], v[92:93], v[96:97]
	v_cvt_pk_bf16_f32 v90, v90, v91
	s_andn2_b64 vcc, exec, s[40:41]
	v_cvt_pk_bf16_f32 v91, v92, v93
	v_pk_mul_f32 v[92:93], v[86:87], s[30:31] op_sel_hi:[1,0]
	s_nop 0
	v_exp_f32_e32 v92, v92
	v_exp_f32_e32 v93, v93
	s_nop 0
	v_pk_add_f32 v[92:93], v[92:93], 1.0 op_sel_hi:[1,0]
	s_nop 0
	v_rcp_f32_e32 v92, v92
	v_rcp_f32_e32 v93, v93
	s_nop 0
	v_pk_mul_f32 v[82:83], v[82:83], v[92:93]
	s_nop 0
	v_cvt_pk_bf16_f32 v92, v82, v83
	v_pk_mul_f32 v[82:83], v[88:89], v[184:185] op_sel_hi:[1,0]
	s_nop 0
	v_pk_mul_f32 v[86:87], v[82:83], s[30:31] op_sel_hi:[1,0]
	v_pk_mul_f32 v[82:83], v[82:83], v[84:85]
	v_exp_f32_e32 v86, v86
	v_exp_f32_e32 v87, v87
	s_nop 0
	v_pk_add_f32 v[86:87], v[86:87], 1.0 op_sel_hi:[1,0]
	s_nop 0
	v_rcp_f32_e32 v86, v86
	v_rcp_f32_e32 v87, v87
	s_nop 0
	v_pk_mul_f32 v[82:83], v[82:83], v[86:87]
	s_nop 0
	v_cvt_pk_bf16_f32 v93, v82, v83
	v_lshl_add_u64 v[82:83], s[16:17], 0, v[150:151]
	v_lshl_add_u64 v[82:83], v[82:83], 0, v[0:1]
	global_store_dwordx4 v[82:83], v[90:93], off nt
	v_pk_mul_f32 v[82:83], v[78:79], s[30:31] op_sel_hi:[1,0]
	v_pk_mul_f32 v[78:79], v[80:81], v[182:183] op_sel_hi:[1,0]
	v_exp_f32_e32 v82, v82
	v_pk_mul_f32 v[80:81], v[78:79], s[30:31] op_sel_hi:[1,0]
	v_exp_f32_e32 v83, v83
	v_exp_f32_e32 v80, v80
	v_exp_f32_e32 v81, v81
	v_pk_mul_f32 v[76:77], v[78:79], v[76:77]
	v_pk_add_f32 v[82:83], v[82:83], 1.0 op_sel_hi:[1,0]
	v_pk_add_f32 v[80:81], v[80:81], 1.0 op_sel_hi:[1,0]
	v_rcp_f32_e32 v82, v82
	v_rcp_f32_e32 v83, v83
	v_rcp_f32_e32 v80, v80
	v_rcp_f32_e32 v81, v81
	v_pk_mul_f32 v[74:75], v[74:75], v[82:83]
	s_nop 0
	v_cvt_pk_bf16_f32 v74, v74, v75
	v_pk_mul_f32 v[76:77], v[76:77], v[80:81]
	s_nop 0
	v_cvt_pk_bf16_f32 v75, v76, v77
	v_pk_mul_f32 v[76:77], v[70:71], s[30:31] op_sel_hi:[1,0]
	s_nop 0
	v_exp_f32_e32 v76, v76
	v_exp_f32_e32 v77, v77
	s_nop 0
	v_pk_add_f32 v[76:77], v[76:77], 1.0 op_sel_hi:[1,0]
	s_nop 0
	v_rcp_f32_e32 v76, v76
	v_rcp_f32_e32 v77, v77
	s_nop 0
	v_pk_mul_f32 v[66:67], v[66:67], v[76:77]
	s_nop 0
	v_cvt_pk_bf16_f32 v76, v66, v67
	v_pk_mul_f32 v[66:67], v[72:73], v[182:183] op_sel_hi:[1,0]
	s_nop 0
	v_pk_mul_f32 v[70:71], v[66:67], s[30:31] op_sel_hi:[1,0]
	v_pk_mul_f32 v[66:67], v[66:67], v[68:69]
	v_exp_f32_e32 v70, v70
	v_exp_f32_e32 v71, v71
	s_nop 0
	v_pk_add_f32 v[70:71], v[70:71], 1.0 op_sel_hi:[1,0]
	s_nop 0
	v_rcp_f32_e32 v70, v70
	v_rcp_f32_e32 v71, v71
	s_nop 0
	v_pk_mul_f32 v[66:67], v[66:67], v[70:71]
	s_nop 0
	v_cvt_pk_bf16_f32 v77, v66, v67
	v_lshl_add_u64 v[66:67], s[16:17], 0, v[152:153]
	v_lshl_add_u64 v[66:67], v[66:67], 0, v[0:1]
	global_store_dwordx4 v[66:67], v[74:77], off nt
	v_pk_mul_f32 v[66:67], v[62:63], s[30:31] op_sel_hi:[1,0]
	v_pk_mul_f32 v[62:63], v[64:65], v[180:181] op_sel_hi:[1,0]
	v_exp_f32_e32 v66, v66
	v_pk_mul_f32 v[64:65], v[62:63], s[30:31] op_sel_hi:[1,0]
	v_exp_f32_e32 v67, v67
	v_exp_f32_e32 v64, v64
	v_exp_f32_e32 v65, v65
	v_pk_mul_f32 v[60:61], v[62:63], v[60:61]
	v_pk_add_f32 v[66:67], v[66:67], 1.0 op_sel_hi:[1,0]
	v_pk_add_f32 v[64:65], v[64:65], 1.0 op_sel_hi:[1,0]
	v_rcp_f32_e32 v66, v66
	v_rcp_f32_e32 v67, v67
	v_rcp_f32_e32 v64, v64
	v_rcp_f32_e32 v65, v65
	v_pk_mul_f32 v[58:59], v[58:59], v[66:67]
	s_nop 0
	v_cvt_pk_bf16_f32 v58, v58, v59
	v_pk_mul_f32 v[60:61], v[60:61], v[64:65]
	s_nop 0
	v_cvt_pk_bf16_f32 v59, v60, v61
	v_pk_mul_f32 v[60:61], v[54:55], s[30:31] op_sel_hi:[1,0]
	s_nop 0
	v_exp_f32_e32 v60, v60
	v_exp_f32_e32 v61, v61
	s_nop 0
	v_pk_add_f32 v[60:61], v[60:61], 1.0 op_sel_hi:[1,0]
	s_nop 0
	v_rcp_f32_e32 v60, v60
	v_rcp_f32_e32 v61, v61
	s_nop 0
	v_pk_mul_f32 v[50:51], v[50:51], v[60:61]
	s_nop 0
	v_cvt_pk_bf16_f32 v60, v50, v51
	v_pk_mul_f32 v[50:51], v[56:57], v[180:181] op_sel_hi:[1,0]
	s_nop 0
	v_pk_mul_f32 v[54:55], v[50:51], s[30:31] op_sel_hi:[1,0]
	v_pk_mul_f32 v[50:51], v[50:51], v[52:53]
	v_exp_f32_e32 v54, v54
	v_exp_f32_e32 v55, v55
	s_nop 0
	v_pk_add_f32 v[54:55], v[54:55], 1.0 op_sel_hi:[1,0]
	s_nop 0
	v_rcp_f32_e32 v54, v54
	v_rcp_f32_e32 v55, v55
	s_nop 0
	v_pk_mul_f32 v[50:51], v[50:51], v[54:55]
	s_nop 0
	v_cvt_pk_bf16_f32 v61, v50, v51
	v_lshl_add_u64 v[50:51], s[16:17], 0, v[154:155]
	v_lshl_add_u64 v[50:51], v[50:51], 0, v[0:1]
	global_store_dwordx4 v[50:51], v[58:61], off nt
	v_pk_mul_f32 v[50:51], v[46:47], s[30:31] op_sel_hi:[1,0]
	v_pk_mul_f32 v[46:47], v[48:49], v[178:179] op_sel_hi:[1,0]
	v_exp_f32_e32 v50, v50
	v_pk_mul_f32 v[48:49], v[46:47], s[30:31] op_sel_hi:[1,0]
	v_exp_f32_e32 v51, v51
	v_exp_f32_e32 v48, v48
	v_exp_f32_e32 v49, v49
	v_pk_mul_f32 v[44:45], v[46:47], v[44:45]
	v_pk_add_f32 v[50:51], v[50:51], 1.0 op_sel_hi:[1,0]
	v_pk_add_f32 v[48:49], v[48:49], 1.0 op_sel_hi:[1,0]
	v_rcp_f32_e32 v50, v50
	v_rcp_f32_e32 v51, v51
	v_rcp_f32_e32 v48, v48
	v_rcp_f32_e32 v49, v49
	v_pk_mul_f32 v[42:43], v[42:43], v[50:51]
	s_nop 0
	v_cvt_pk_bf16_f32 v42, v42, v43
	v_pk_mul_f32 v[44:45], v[44:45], v[48:49]
	s_nop 0
	v_cvt_pk_bf16_f32 v43, v44, v45
	v_pk_mul_f32 v[44:45], v[38:39], s[30:31] op_sel_hi:[1,0]
	s_nop 0
	v_exp_f32_e32 v44, v44
	v_exp_f32_e32 v45, v45
	s_nop 0
	v_pk_add_f32 v[44:45], v[44:45], 1.0 op_sel_hi:[1,0]
	s_nop 0
	v_rcp_f32_e32 v44, v44
	v_rcp_f32_e32 v45, v45
	s_nop 0
	v_pk_mul_f32 v[34:35], v[34:35], v[44:45]
	s_nop 0
	v_cvt_pk_bf16_f32 v44, v34, v35
	v_pk_mul_f32 v[34:35], v[40:41], v[178:179] op_sel_hi:[1,0]
	s_nop 0
	v_pk_mul_f32 v[38:39], v[34:35], s[30:31] op_sel_hi:[1,0]
	v_pk_mul_f32 v[34:35], v[34:35], v[36:37]
	v_exp_f32_e32 v38, v38
	v_exp_f32_e32 v39, v39
	s_nop 0
	v_pk_add_f32 v[38:39], v[38:39], 1.0 op_sel_hi:[1,0]
	s_nop 0
	v_rcp_f32_e32 v38, v38
	v_rcp_f32_e32 v39, v39
	s_nop 0
	v_pk_mul_f32 v[34:35], v[34:35], v[38:39]
	s_nop 0
	v_cvt_pk_bf16_f32 v45, v34, v35
	v_lshl_add_u64 v[34:35], s[16:17], 0, v[156:157]
	v_lshl_add_u64 v[34:35], v[34:35], 0, v[0:1]
	global_store_dwordx4 v[34:35], v[42:45], off nt
	v_pk_mul_f32 v[34:35], v[30:31], s[30:31] op_sel_hi:[1,0]
	v_pk_mul_f32 v[30:31], v[32:33], v[132:133] op_sel_hi:[1,0]
	v_exp_f32_e32 v34, v34
	v_pk_mul_f32 v[32:33], v[30:31], s[30:31] op_sel_hi:[1,0]
	v_exp_f32_e32 v35, v35
	v_exp_f32_e32 v32, v32
	v_exp_f32_e32 v33, v33
	v_pk_mul_f32 v[28:29], v[30:31], v[28:29]
	v_pk_add_f32 v[34:35], v[34:35], 1.0 op_sel_hi:[1,0]
	v_pk_add_f32 v[32:33], v[32:33], 1.0 op_sel_hi:[1,0]
	v_rcp_f32_e32 v34, v34
	v_rcp_f32_e32 v35, v35
	v_rcp_f32_e32 v32, v32
	v_rcp_f32_e32 v33, v33
	v_pk_mul_f32 v[26:27], v[26:27], v[34:35]
	s_nop 0
	v_cvt_pk_bf16_f32 v26, v26, v27
	v_pk_mul_f32 v[28:29], v[28:29], v[32:33]
	s_nop 0
	v_cvt_pk_bf16_f32 v27, v28, v29
	v_pk_mul_f32 v[28:29], v[22:23], s[30:31] op_sel_hi:[1,0]
	s_nop 0
	v_exp_f32_e32 v28, v28
	v_exp_f32_e32 v29, v29
	s_nop 0
	v_pk_add_f32 v[28:29], v[28:29], 1.0 op_sel_hi:[1,0]
	s_nop 0
	v_rcp_f32_e32 v28, v28
	v_rcp_f32_e32 v29, v29
	s_nop 0
	v_pk_mul_f32 v[18:19], v[18:19], v[28:29]
	s_nop 0
	v_cvt_pk_bf16_f32 v28, v18, v19
	v_pk_mul_f32 v[18:19], v[24:25], v[132:133] op_sel_hi:[1,0]
	s_nop 0
	v_pk_mul_f32 v[22:23], v[18:19], s[30:31] op_sel_hi:[1,0]
	v_pk_mul_f32 v[18:19], v[18:19], v[20:21]
	v_exp_f32_e32 v22, v22
	v_exp_f32_e32 v23, v23
	s_nop 0
	v_pk_add_f32 v[22:23], v[22:23], 1.0 op_sel_hi:[1,0]
	s_nop 0
	v_rcp_f32_e32 v22, v22
	v_rcp_f32_e32 v23, v23
	s_nop 0
	v_pk_mul_f32 v[18:19], v[18:19], v[22:23]
	s_nop 0
	v_cvt_pk_bf16_f32 v29, v18, v19
	v_lshl_add_u64 v[18:19], s[16:17], 0, v[158:159]
	v_lshl_add_u64 v[18:19], v[18:19], 0, v[0:1]
	global_store_dwordx4 v[18:19], v[26:29], off nt
	v_pk_mul_f32 v[18:19], v[14:15], s[30:31] op_sel_hi:[1,0]
	v_pk_mul_f32 v[14:15], v[16:17], v[130:131] op_sel_hi:[1,0]
	v_exp_f32_e32 v18, v18
	v_pk_mul_f32 v[16:17], v[14:15], s[30:31] op_sel_hi:[1,0]
	v_exp_f32_e32 v19, v19
	v_exp_f32_e32 v16, v16
	v_exp_f32_e32 v17, v17
	v_pk_mul_f32 v[12:13], v[14:15], v[12:13]
	v_pk_add_f32 v[18:19], v[18:19], 1.0 op_sel_hi:[1,0]
	v_pk_add_f32 v[16:17], v[16:17], 1.0 op_sel_hi:[1,0]
	v_rcp_f32_e32 v18, v18
	v_rcp_f32_e32 v19, v19
	v_rcp_f32_e32 v16, v16
	v_rcp_f32_e32 v17, v17
	v_pk_mul_f32 v[10:11], v[10:11], v[18:19]
	s_nop 0
	v_cvt_pk_bf16_f32 v10, v10, v11
	v_pk_mul_f32 v[12:13], v[12:13], v[16:17]
	s_nop 0
	v_cvt_pk_bf16_f32 v11, v12, v13
	v_pk_mul_f32 v[12:13], v[6:7], s[30:31] op_sel_hi:[1,0]
	s_nop 0
	v_exp_f32_e32 v12, v12
	v_exp_f32_e32 v13, v13
	s_nop 0
	v_pk_add_f32 v[12:13], v[12:13], 1.0 op_sel_hi:[1,0]
	s_nop 0
	v_rcp_f32_e32 v12, v12
	v_rcp_f32_e32 v13, v13
	s_nop 0
	v_pk_mul_f32 v[2:3], v[2:3], v[12:13]
	s_nop 0
	v_cvt_pk_bf16_f32 v12, v2, v3
	v_pk_mul_f32 v[2:3], v[8:9], v[130:131] op_sel_hi:[1,0]
	s_nop 0
	v_pk_mul_f32 v[6:7], v[2:3], s[30:31] op_sel_hi:[1,0]
	v_pk_mul_f32 v[2:3], v[2:3], v[4:5]
	v_exp_f32_e32 v6, v6
	v_exp_f32_e32 v7, v7
	s_nop 0
	v_pk_add_f32 v[6:7], v[6:7], 1.0 op_sel_hi:[1,0]
	s_nop 0
	v_rcp_f32_e32 v6, v6
	v_rcp_f32_e32 v7, v7
	s_nop 0
	v_pk_mul_f32 v[2:3], v[2:3], v[6:7]
	s_nop 0
	v_cvt_pk_bf16_f32 v13, v2, v3
	v_lshl_add_u64 v[2:3], s[16:17], 0, v[160:161]
	v_lshl_add_u64 v[2:3], v[2:3], 0, v[0:1]
	global_store_dwordx4 v[2:3], v[10:13], off nt
	s_mov_b64 s[16:17], -1
	s_cbranch_vccnz .LBB7_352
	s_andn2_b64 vcc, exec, s[50:51]
	s_cbranch_vccnz .LBB7_351
	s_barrier
	s_branch .LBB7_351
.LBB7_363:
	v_mov_b32_e32 v129, 0
	v_mov_b32_e32 v128, v129
	v_mov_b32_e32 v127, v129
	v_mov_b32_e32 v126, v129
	v_mov_b32_e32 v121, v129
	v_mov_b32_e32 v120, v129
	v_mov_b32_e32 v119, v129
	v_mov_b32_e32 v118, v129
	v_mov_b32_e32 v113, v129
	v_mov_b32_e32 v112, v129
	v_mov_b32_e32 v111, v129
	v_mov_b32_e32 v110, v129
	v_mov_b32_e32 v105, v129
	v_mov_b32_e32 v104, v129
	v_mov_b32_e32 v103, v129
	v_mov_b32_e32 v102, v129
	v_mov_b32_e32 v97, v129
	v_mov_b32_e32 v96, v129
	v_mov_b32_e32 v95, v129
	v_mov_b32_e32 v94, v129
	v_mov_b32_e32 v89, v129
	v_mov_b32_e32 v88, v129
	v_mov_b32_e32 v87, v129
	v_mov_b32_e32 v86, v129
	v_mov_b32_e32 v81, v129
	v_mov_b32_e32 v80, v129
	v_mov_b32_e32 v79, v129
	v_mov_b32_e32 v78, v129
	v_mov_b32_e32 v73, v129
	v_mov_b32_e32 v72, v129
	v_mov_b32_e32 v71, v129
	v_mov_b32_e32 v70, v129
	v_mov_b32_e32 v125, v129
	v_mov_b32_e32 v124, v129
	v_mov_b32_e32 v123, v129
	v_mov_b32_e32 v122, v129
	v_mov_b32_e32 v117, v129
	v_mov_b32_e32 v116, v129
	v_mov_b32_e32 v115, v129
	v_mov_b32_e32 v114, v129
	v_mov_b32_e32 v109, v129
	v_mov_b32_e32 v108, v129
	v_mov_b32_e32 v107, v129
	v_mov_b32_e32 v106, v129
	v_mov_b32_e32 v101, v129
	v_mov_b32_e32 v100, v129
	v_mov_b32_e32 v99, v129
	v_mov_b32_e32 v98, v129
	v_mov_b32_e32 v93, v129
	v_mov_b32_e32 v92, v129
	v_mov_b32_e32 v91, v129
	v_mov_b32_e32 v90, v129
	v_mov_b32_e32 v85, v129
	v_mov_b32_e32 v84, v129
	v_mov_b32_e32 v83, v129
	v_mov_b32_e32 v82, v129
	v_mov_b32_e32 v77, v129
	v_mov_b32_e32 v76, v129
	v_mov_b32_e32 v75, v129
	v_mov_b32_e32 v74, v129
	v_mov_b32_e32 v69, v129
	v_mov_b32_e32 v68, v129
	v_mov_b32_e32 v67, v129
	v_mov_b32_e32 v66, v129
	v_mov_b32_e32 v65, v129
	v_mov_b32_e32 v64, v129
	v_mov_b32_e32 v63, v129
	v_mov_b32_e32 v62, v129
	v_mov_b32_e32 v57, v129
	v_mov_b32_e32 v56, v129
	v_mov_b32_e32 v55, v129
	v_mov_b32_e32 v54, v129
	v_mov_b32_e32 v49, v129
	v_mov_b32_e32 v48, v129
	v_mov_b32_e32 v47, v129
	v_mov_b32_e32 v46, v129
	v_mov_b32_e32 v41, v129
	v_mov_b32_e32 v40, v129
	v_mov_b32_e32 v39, v129
	v_mov_b32_e32 v38, v129
	v_mov_b32_e32 v33, v129
	v_mov_b32_e32 v32, v129
	v_mov_b32_e32 v31, v129
	v_mov_b32_e32 v30, v129
	v_mov_b32_e32 v25, v129
	v_mov_b32_e32 v24, v129
	v_mov_b32_e32 v23, v129
	v_mov_b32_e32 v22, v129
	v_mov_b32_e32 v17, v129
	v_mov_b32_e32 v16, v129
	v_mov_b32_e32 v15, v129
	v_mov_b32_e32 v14, v129
	v_mov_b32_e32 v9, v129
	v_mov_b32_e32 v8, v129
	v_mov_b32_e32 v7, v129
	v_mov_b32_e32 v6, v129
	v_mov_b32_e32 v61, v129
	v_mov_b32_e32 v60, v129
	v_mov_b32_e32 v59, v129
	v_mov_b32_e32 v58, v129
	v_mov_b32_e32 v53, v129
	v_mov_b32_e32 v52, v129
	v_mov_b32_e32 v51, v129
	v_mov_b32_e32 v50, v129
	v_mov_b32_e32 v45, v129
	v_mov_b32_e32 v44, v129
	v_mov_b32_e32 v43, v129
	v_mov_b32_e32 v42, v129
	v_mov_b32_e32 v37, v129
	v_mov_b32_e32 v36, v129
	v_mov_b32_e32 v35, v129
	v_mov_b32_e32 v34, v129
	v_mov_b32_e32 v29, v129
	v_mov_b32_e32 v28, v129
	v_mov_b32_e32 v27, v129
	v_mov_b32_e32 v26, v129
	v_mov_b32_e32 v21, v129
	v_mov_b32_e32 v20, v129
	v_mov_b32_e32 v19, v129
	v_mov_b32_e32 v18, v129
	v_mov_b32_e32 v13, v129
	v_mov_b32_e32 v12, v129
	v_mov_b32_e32 v11, v129
	v_mov_b32_e32 v10, v129
	v_mov_b32_e32 v5, v129
	v_mov_b32_e32 v4, v129
	v_mov_b32_e32 v3, v129
	v_mov_b32_e32 v2, v129
	s_branch .Lswi_pref
